# v45 plus: weight-conversion prologue no longer waits vmcnt(1)/(0) between the next item's load groups on the no-gain-vector path (w_out, w_down)
# baseline (speedup 1.0000x reference)
.LBB0_49:
	v_mov_b32_e32 v85, 1.0
	v_mov_b32_e32 v87, 1.0

.LBB0_52:
	v_mov_b32_e32 v92, 1.0
	v_mov_b32_e32 v93, 1.0

.LBB0_55:
	v_mov_b32_e32 v94, 1.0
	v_mov_b32_e32 v95, 1.0

.LBB0_58:
	v_mov_b32_e32 v96, 1.0
	v_mov_b32_e32 v97, 1.0
